# STAGGER-P2 offset tuned to 2.5 sleeps (about half a K-loop+epilogue period) instead of 3 (on REL-FIRST)
# speedup vs baseline: 1.0035x; 1.0009x over previous
.LBB0_201:
	s_cmp_lt_i32 s62, 3
	s_cselect_b64 s[0:1], -1, 0
	s_and_b64 s[8:9], s[0:1], s[4:5]
	s_andn2_b64 vcc, exec, s[8:9]
	s_cbranch_vccnz .LBB0_266
	s_cmpk_lt_i32 s75, 0x50
	s_cbranch_scc1 .Lstagp2_go
	s_sleep 127
	s_sleep 127
	s_sleep 64
